# v6 plus diff-attention loop rescheduled the same way (S0 chain first, in-place softmax, LDS stores under PV1, barrier before last 3 MFMAs)
# speedup vs baseline: 1.0088x; 1.0031x over previous
; #define MFMA(a, b, c) __builtin_amdgcn_mfma_f32_32x32x16_bf16((a), (b), (c), 0, 0, 0)
; template <int DQK, bool ALIBI>
; DI void attn_pass(const u16* __restrict__ Qp, int ldq, const u16* __restrict__ Kp, int ldk, const u16* __restrict__ VTp,
;                   int seq_start, int kt_lo, int kt_hi, int q0, float slope2, f32x16 (&O)[4], float& lsum, char* lds) {
;     ...
;     for (int ks = 0; ks < NKS; ++ks) {
;       k0[ks] = *(const bf16x8*)(Ks + r * KST + ks * 16 + h * 8);
;       k1[ks] = *(const bf16x8*)(Ks + (32 + r) * KST + ks * 16 + h * 8);
;     }
;     __builtin_amdgcn_sched_barrier(0);
; #pragma unroll
;     for (int ks = 0; ks < NKS; ++ks) {
;       S0 = MFMA(k0[ks], qf[ks], S0);
;       S1 = MFMA(k1[ks], qf[ks], S1);
;     }
;     if (kt + 1 < kt_hi) ATT_LSTORE(cur ^ 1);
;     if (kt + 2 < kt_hi) ATT_GLOAD(kt + 2);
; #pragma unroll
;     for (int s = 0; s < 2; ++s)
; #pragma unroll
;       for (int db = 0; db < 4; ++db) vf[s][db] = *(const bf16x8*)(Vs + (db * 32 + r) * 72 + s * 16 + h * 8);
;     __builtin_amdgcn_sched_barrier(0);
;     bf16x8 pf[2];
;     ...
;     ATT_SOFTMAX(S0);
;     __builtin_amdgcn_sched_barrier(0);
; #pragma unroll
;     for (int s = 0; s < 2; ++s)
; #pragma unroll
;       for (int db = 0; db < 4; ++db) O[db] = MFMA(vf[s][db], pf[s], O[db]);
;     bf16x8 vg[2][4];
; #pragma unroll
;     for (int s = 0; s < 2; ++s)
; #pragma unroll
;       for (int db = 0; db < 4; ++db) vg[s][db] = *(const bf16x8*)(Vs + (db * 32 + r) * 72 + 32 + s * 16 + h * 8);
;     bf16x8 pg[2];
;     {
;       float pv[16];
; #pragma unroll
;       for (int i = 0; i < 16; ++i) pv[i] = __builtin_amdgcn_exp2f(S1[i]);
; #pragma unroll
;       for (int i = 0; i < 8; ++i) l2 += f32x2{pv[2 * i], pv[2 * i + 1]};
; #pragma unroll
;       for (int s = 0; s < 2; ++s) {
;         u32 a0 = pack2(pv[8 * s], pv[8 * s + 1]), a1 = pack2(pv[8 * s + 2], pv[8 * s + 3]);
;         u32 a2 = pack2(pv[8 * s + 4], pv[8 * s + 5]), a3 = pack2(pv[8 * s + 6], pv[8 * s + 7]);
;         u32x4 pk = {a0, a1, a2, a3};
;         pg[s] = __builtin_bit_cast(bf16x8, pk);
;       }
;     }
.LBB0_1153:
	s_or_b64 exec, exec, s[6:7]
	s_and_b32 s6, s87, 1
	s_mul_i32 s44, s6, 0x6c00
	v_add_u32_e32 v131, s44, v156
	v_lshl_add_u32 v144, v153, 1, v131
	ds_read_b128 v[160:163], v144
	ds_read_b128 v[164:167], v144 offset:32
	ds_read_b128 v[176:179], v144 offset:64
	ds_read_b128 v[180:183], v144 offset:96
	ds_read_b128 v[168:171], v144 offset:4608
	ds_read_b128 v[172:175], v144 offset:4640
	ds_read_b128 v[184:187], v144 offset:4672
	ds_read_b128 v[194:197], v144 offset:4704
	s_waitcnt lgkmcnt(7)
	v_mfma_f32_32x32x16_bf16 v[82:97], v[160:163], v[98:101], v[82:97]
	s_waitcnt lgkmcnt(6)
	v_mfma_f32_32x32x16_bf16 v[82:97], v[164:167], v[102:105], v[82:97]
	s_waitcnt lgkmcnt(5)
	v_mfma_f32_32x32x16_bf16 v[82:97], v[176:179], v[106:109], v[82:97]
	s_waitcnt lgkmcnt(4)
	v_mfma_f32_32x32x16_bf16 v[82:97], v[180:183], v[110:113], v[82:97]
	s_waitcnt lgkmcnt(3)
	v_mfma_f32_32x32x16_bf16 v[66:81], v[168:171], v[98:101], v[66:81]
	s_waitcnt lgkmcnt(2)
	v_mfma_f32_32x32x16_bf16 v[66:81], v[172:175], v[102:105], v[66:81]
	v_add3_u32 v144, s44, v0, v156
	ds_read_b128 v[160:163], v144 offset:9216
	ds_read_b128 v[164:167], v144 offset:9248
	ds_read_b128 v[168:171], v144 offset:13824
	ds_read_b128 v[172:175], v144 offset:13856
	ds_read_b128 v[176:179], v144 offset:18432
	ds_read_b128 v[180:183], v144 offset:18464
	s_waitcnt lgkmcnt(7)
	v_mfma_f32_32x32x16_bf16 v[66:81], v[184:187], v[106:109], v[66:81]
	v_exp_f32_e32 v82, v82
	v_exp_f32_e32 v83, v83
	v_exp_f32_e32 v84, v84
	v_exp_f32_e32 v85, v85
	s_waitcnt lgkmcnt(6)
	v_mfma_f32_32x32x16_bf16 v[66:81], v[194:197], v[110:113], v[66:81]
	ds_read_b128 v[184:187], v144 offset:23040
	ds_read_b128 v[194:197], v144 offset:23072
	v_exp_f32_e32 v86, v86
	v_exp_f32_e32 v87, v87
	v_exp_f32_e32 v88, v88
	v_exp_f32_e32 v89, v89
	v_exp_f32_e32 v90, v90
	v_exp_f32_e32 v91, v91
	v_exp_f32_e32 v92, v92
	v_exp_f32_e32 v93, v93
	v_exp_f32_e32 v94, v94
	v_exp_f32_e32 v95, v95
	v_exp_f32_e32 v96, v96
	v_exp_f32_e32 v97, v97
	v_add_f32_e32 v142, v142, v82
	v_add_f32_e32 v143, v143, v83
	v_add_f32_e32 v142, v84, v142
	v_add_f32_e32 v143, v85, v143
	v_add_f32_e32 v142, v86, v142
	v_add_f32_e32 v143, v87, v143
	v_add_f32_e32 v142, v88, v142
	v_add_f32_e32 v143, v89, v143
	v_add_f32_e32 v142, v90, v142
	v_add_f32_e32 v143, v91, v143
	v_add_f32_e32 v142, v92, v142
	v_add_f32_e32 v143, v93, v143
	v_add_f32_e32 v142, v94, v142
	v_add_f32_e32 v143, v95, v143
	v_add_f32_e32 v142, v96, v142
	v_add_f32_e32 v143, v97, v143
	v_cvt_pk_bf16_f32 v82, v82, v83
	v_cvt_pk_bf16_f32 v83, v84, v85
	v_cvt_pk_bf16_f32 v84, v86, v87
	v_cvt_pk_bf16_f32 v85, v88, v89
	v_cvt_pk_bf16_f32 v86, v90, v91
	v_cvt_pk_bf16_f32 v87, v92, v93
	v_cvt_pk_bf16_f32 v88, v94, v95
	v_cvt_pk_bf16_f32 v89, v96, v97
	s_waitcnt lgkmcnt(7)
	v_mfma_f32_32x32x16_bf16 v[50:65], v[160:163], v[82:85], v[50:65]
	v_exp_f32_e32 v66, v66
	v_exp_f32_e32 v67, v67
	v_exp_f32_e32 v68, v68
	v_exp_f32_e32 v69, v69
	s_waitcnt lgkmcnt(5)
	v_mfma_f32_32x32x16_bf16 v[34:49], v[168:171], v[82:85], v[34:49]
	v_exp_f32_e32 v70, v70
	v_exp_f32_e32 v71, v71
	v_exp_f32_e32 v72, v72
	v_exp_f32_e32 v73, v73
	s_waitcnt lgkmcnt(3)
	v_mfma_f32_32x32x16_bf16 v[18:33], v[176:179], v[82:85], v[18:33]
	v_exp_f32_e32 v74, v74
	v_exp_f32_e32 v75, v75
	v_exp_f32_e32 v76, v76
	v_exp_f32_e32 v77, v77
	v_mfma_f32_32x32x16_bf16 v[50:65], v[164:167], v[86:89], v[50:65]
	ds_read_b128 v[160:163], v144 offset:9312
	ds_read_b128 v[168:171], v144 offset:18528
	v_exp_f32_e32 v78, v78
	v_exp_f32_e32 v79, v79
	v_exp_f32_e32 v80, v80
	v_exp_f32_e32 v81, v81
	v_mfma_f32_32x32x16_bf16 v[34:49], v[172:175], v[86:89], v[34:49]
	ds_read_b128 v[164:167], v144 offset:13920
	ds_read_b128 v[90:93], v144 offset:18496
	ds_read_b128 v[94:97], v144 offset:23104
	v_add_f32_e32 v142, v66, v142
	v_add_f32_e32 v143, v67, v143
	v_add_f32_e32 v142, v68, v142
	v_add_f32_e32 v143, v69, v143
	s_waitcnt lgkmcnt(7)
	v_mfma_f32_32x32x16_bf16 v[18:33], v[180:183], v[86:89], v[18:33]
	ds_read_b128 v[198:201], v144 offset:9280
	v_add_f32_e32 v142, v70, v142
	v_add_f32_e32 v143, v71, v143
	v_add_f32_e32 v142, v72, v142
	v_add_f32_e32 v143, v73, v143
	s_waitcnt lgkmcnt(7)
	v_mfma_f32_32x32x16_bf16 v[2:17], v[184:187], v[82:85], v[2:17]
	v_add_f32_e32 v142, v74, v142
	v_add_f32_e32 v143, v75, v143
	v_add_f32_e32 v142, v76, v142
	v_add_f32_e32 v143, v77, v143
	s_waitcnt lgkmcnt(6)
	v_mfma_f32_32x32x16_bf16 v[2:17], v[194:197], v[86:89], v[2:17]
	ds_read_b128 v[86:89], v144 offset:13888
	ds_read_b128 v[82:85], v144 offset:23136
	v_add_f32_e32 v142, v78, v142
	v_add_f32_e32 v143, v79, v143
	v_add_f32_e32 v142, v80, v142
	v_add_f32_e32 v143, v81, v143
	v_cvt_pk_bf16_f32 v66, v66, v67
	v_cvt_pk_bf16_f32 v67, v68, v69
	v_cvt_pk_bf16_f32 v68, v70, v71
	v_cvt_pk_bf16_f32 v69, v72, v73
	v_cvt_pk_bf16_f32 v70, v74, v75
	v_cvt_pk_bf16_f32 v71, v76, v77
	v_cvt_pk_bf16_f32 v72, v78, v79
	v_cvt_pk_bf16_f32 v73, v80, v81
	s_waitcnt lgkmcnt(2)
	v_mfma_f32_32x32x16_bf16 v[50:65], v[198:201], v[66:69], v[50:65]
	s_waitcnt lgkmcnt(1)
	v_mfma_f32_32x32x16_bf16 v[34:49], v[86:89], v[66:69], v[34:49]
	s_waitcnt lgkmcnt(0)
	s_add_i32 s45, s73, s87
	s_add_i32 s7, s45, 1
	s_cmp_ge_i32 s7, s77
	s_cbranch_scc1 .Lmy_dif_w2
	s_and_b32 s6, s87, 1
	s_xor_b32 s46, s6, 1
	s_mulk_i32 s46, 0x6c00
	s_and_saveexec_b64 s[6:7], s[42:43]
	s_cbranch_execz .Lmy_dif_w1
	v_add3_u32 v144, s46, v157, v158
	s_waitcnt vmcnt(2)
	ds_write_b128 v144, v[114:117]

; #define MFMA(a, b, c) __builtin_amdgcn_mfma_f32_32x32x16_bf16((a), (b), (c), 0, 0, 0)
; template <int DQK, bool ALIBI>
; DI void attn_pass(const u16* __restrict__ Qp, int ldq, const u16* __restrict__ Kp, int ldk, const u16* __restrict__ VTp,
;                   int seq_start, int kt_lo, int kt_hi, int q0, float slope2, f32x16 (&O)[4], float& lsum, char* lds) {
;     ...
; #pragma unroll
;     for (int s = 0; s < 2; ++s)
; #pragma unroll
;       for (int db = 0; db < 4; ++db) O[db] = MFMA(vg[s][db], pg[s], O[db]);
;     __syncthreads();
.Lmy_dif_g2:
	s_add_i32 s87, s87, 1
	s_add_i32 s6, s73, s87
	v_lshl_add_u64 v[138:139], v[138:139], 0, s[80:81]
	v_lshl_add_u64 v[140:141], v[140:141], 0, s[80:81]
	s_cmp_lt_i32 s6, s77
	v_mfma_f32_32x32x16_bf16 v[18:33], v[90:93], v[66:69], v[18:33]
	v_mfma_f32_32x32x16_bf16 v[2:17], v[94:97], v[66:69], v[2:17]
	v_mfma_f32_32x32x16_bf16 v[50:65], v[160:163], v[70:73], v[50:65]
	s_waitcnt lgkmcnt(0)
	s_barrier
	v_mfma_f32_32x32x16_bf16 v[34:49], v[164:167], v[70:73], v[34:49]
	v_mfma_f32_32x32x16_bf16 v[18:33], v[168:171], v[70:73], v[18:33]
	v_mfma_f32_32x32x16_bf16 v[2:17], v[82:85], v[70:73], v[2:17]
	s_cbranch_scc0 .LBB0_1163
	s_mov_b32 s89, s88
	s_branch .LBB0_1149
